# v063 + P1 cache k/v row loads issued together + P7 epilogue canonicalising v_max removed (prologue/epilogue trimming)
# baseline (speedup 1.0000x reference)
.LBB0_804:
	v_max_f32_e32 v126, 0, v126
	v_max_f32_e32 v127, 0, v127
	v_max_f32_e32 v122, 0, v122
	v_mul_f32_e32 v126, v126, v126
	v_max_f32_e32 v123, 0, v123
	v_mul_f32_e32 v127, v127, v127
	v_max_f32_e32 v128, 0, v128
	v_max_f32_e32 v124, 0, v124
	v_max_f32_e32 v129, 0, v129
	v_max_f32_e32 v125, 0, v125
	v_mul_f32_e32 v122, v122, v122
	v_mul_f32_e32 v123, v123, v123
	v_mul_f32_e32 v128, v128, v128
	v_mul_f32_e32 v124, v124, v124
	v_mul_f32_e32 v129, v129, v129
	v_mul_f32_e32 v125, v125, v125
	v_cvt_pk_bf16_f32 v126, v126, v127
	v_cvt_pk_bf16_f32 v127, v128, v129
	v_readlane_b32 s2, v249, 53
	v_cvt_pk_bf16_f32 v122, v122, v123
	v_cvt_pk_bf16_f32 v123, v124, v125
	ds_bpermute_b32 v124, v142, v126
	ds_bpermute_b32 v125, v142, v127
	ds_bpermute_b32 v126, v142, v122
	ds_bpermute_b32 v127, v142, v123
	v_lshl_or_b32 v148, s40, 8, v144
	v_readlane_b32 s3, v249, 54
	v_lshl_add_u32 v147, s88, 8, v143
	v_ashrrev_i32_e32 v149, 31, v148
	v_mov_b64_e32 v[140:141], s[2:3]
	v_mad_i64_i32 v[128:129], s[2:3], v147, s85, v[140:141]
	v_lshlrev_b64 v[122:123], 1, v[148:149]
	v_max_f32_e32 v118, 0, v118
	v_max_f32_e32 v119, 0, v119
	v_max_f32_e32 v120, 0, v120
	v_max_f32_e32 v117, 0, v117
	v_lshl_add_u64 v[128:129], v[128:129], 0, v[122:123]
	v_max_f32_e32 v114, 0, v114
	v_mul_f32_e32 v118, v118, v118
	v_max_f32_e32 v115, 0, v115
	v_mul_f32_e32 v119, v119, v119
	v_max_f32_e32 v116, 0, v116
	v_mul_f32_e32 v120, v120, v120
	v_max_f32_e32 v121, 0, v121
	v_mul_f32_e32 v117, v117, v117
	s_waitcnt lgkmcnt(0)
	global_store_dwordx4 v[128:129], v[124:127], off
	v_mul_f32_e32 v114, v114, v114
	v_mul_f32_e32 v115, v115, v115
	v_mul_f32_e32 v116, v116, v116
	v_mul_f32_e32 v121, v121, v121
	v_cvt_pk_bf16_f32 v118, v118, v119
	v_cvt_pk_bf16_f32 v119, v120, v121
	v_cvt_pk_bf16_f32 v120, v114, v115
	v_cvt_pk_bf16_f32 v117, v116, v117
	ds_bpermute_b32 v114, v142, v118
	ds_bpermute_b32 v115, v142, v119
	ds_bpermute_b32 v116, v142, v120
	ds_bpermute_b32 v117, v142, v117
	v_max_f32_e32 v110, 0, v110
	v_max_f32_e32 v111, 0, v111
	v_max_f32_e32 v112, 0, v112
	v_max_f32_e32 v109, 0, v109
	v_max_f32_e32 v106, 0, v106
	v_mul_f32_e32 v110, v110, v110
	v_max_f32_e32 v107, 0, v107
	v_mul_f32_e32 v111, v111, v111
	v_max_f32_e32 v108, 0, v108
	v_mul_f32_e32 v112, v112, v112
	v_max_f32_e32 v113, 0, v113
	v_mul_f32_e32 v109, v109, v109
	s_waitcnt lgkmcnt(0)
	global_store_dwordx4 v[128:129], v[114:117], off offset:256
	v_mul_f32_e32 v106, v106, v106
	v_mul_f32_e32 v107, v107, v107
	v_mul_f32_e32 v108, v108, v108
	v_mul_f32_e32 v113, v113, v113
	v_cvt_pk_bf16_f32 v110, v110, v111
	v_cvt_pk_bf16_f32 v111, v112, v113
	v_cvt_pk_bf16_f32 v112, v106, v107
	v_cvt_pk_bf16_f32 v109, v108, v109
	ds_bpermute_b32 v106, v142, v110
	ds_bpermute_b32 v107, v142, v111
	ds_bpermute_b32 v108, v142, v112
	ds_bpermute_b32 v109, v142, v109
	v_or_b32_e32 v110, 16, v147
	v_mad_i64_i32 v[110:111], s[2:3], v110, s85, v[140:141]
	v_max_f32_e32 v102, 0, v102
	v_max_f32_e32 v103, 0, v103
	v_max_f32_e32 v104, 0, v104
	v_max_f32_e32 v101, 0, v101
	v_lshl_add_u64 v[110:111], v[110:111], 0, v[122:123]
	v_max_f32_e32 v98, 0, v98
	v_mul_f32_e32 v102, v102, v102
	v_max_f32_e32 v99, 0, v99
	v_mul_f32_e32 v103, v103, v103
	v_max_f32_e32 v100, 0, v100
	v_mul_f32_e32 v104, v104, v104
	v_max_f32_e32 v105, 0, v105
	v_mul_f32_e32 v101, v101, v101
	s_waitcnt lgkmcnt(0)
	global_store_dwordx4 v[110:111], v[106:109], off
	v_mul_f32_e32 v98, v98, v98
	v_mul_f32_e32 v99, v99, v99
	v_mul_f32_e32 v100, v100, v100
	v_mul_f32_e32 v105, v105, v105
	v_cvt_pk_bf16_f32 v102, v102, v103
	v_cvt_pk_bf16_f32 v103, v104, v105
	v_cvt_pk_bf16_f32 v104, v98, v99
	v_cvt_pk_bf16_f32 v101, v100, v101
	ds_bpermute_b32 v98, v142, v102
	ds_bpermute_b32 v99, v142, v103
	ds_bpermute_b32 v100, v142, v104
	ds_bpermute_b32 v101, v142, v101
	v_max_f32_e32 v94, 0, v94
	v_max_f32_e32 v95, 0, v95
	v_max_f32_e32 v96, 0, v96
	v_max_f32_e32 v93, 0, v93
	v_max_f32_e32 v90, 0, v90
	v_mul_f32_e32 v94, v94, v94
	v_max_f32_e32 v91, 0, v91
	v_mul_f32_e32 v95, v95, v95
	v_max_f32_e32 v92, 0, v92
	v_mul_f32_e32 v96, v96, v96
	v_max_f32_e32 v97, 0, v97
	v_mul_f32_e32 v93, v93, v93
	s_waitcnt lgkmcnt(0)
	global_store_dwordx4 v[110:111], v[98:101], off offset:256
	v_mul_f32_e32 v90, v90, v90
	v_mul_f32_e32 v91, v91, v91
	v_mul_f32_e32 v92, v92, v92
	v_mul_f32_e32 v97, v97, v97
	v_cvt_pk_bf16_f32 v94, v94, v95
	v_cvt_pk_bf16_f32 v95, v96, v97
	v_cvt_pk_bf16_f32 v96, v90, v91
	v_cvt_pk_bf16_f32 v93, v92, v93
	ds_bpermute_b32 v90, v142, v94
	ds_bpermute_b32 v91, v142, v95
	ds_bpermute_b32 v92, v142, v96
	ds_bpermute_b32 v93, v142, v93
	v_or_b32_e32 v94, 32, v147
	v_mad_i64_i32 v[94:95], s[2:3], v94, s85, v[140:141]
	v_max_f32_e32 v86, 0, v86
	v_max_f32_e32 v87, 0, v87
	v_max_f32_e32 v88, 0, v88
	v_max_f32_e32 v85, 0, v85
	v_lshl_add_u64 v[94:95], v[94:95], 0, v[122:123]
	v_max_f32_e32 v82, 0, v82
	v_mul_f32_e32 v86, v86, v86
	v_max_f32_e32 v83, 0, v83
	v_mul_f32_e32 v87, v87, v87
	v_max_f32_e32 v84, 0, v84
	v_mul_f32_e32 v88, v88, v88
	v_max_f32_e32 v89, 0, v89
	v_mul_f32_e32 v85, v85, v85
	s_waitcnt lgkmcnt(0)
	global_store_dwordx4 v[94:95], v[90:93], off
	v_mul_f32_e32 v82, v82, v82
	v_mul_f32_e32 v83, v83, v83
	v_mul_f32_e32 v84, v84, v84
	v_mul_f32_e32 v89, v89, v89
	v_cvt_pk_bf16_f32 v86, v86, v87
	v_cvt_pk_bf16_f32 v87, v88, v89
	v_cvt_pk_bf16_f32 v88, v82, v83
	v_cvt_pk_bf16_f32 v85, v84, v85
	ds_bpermute_b32 v82, v142, v86
	ds_bpermute_b32 v83, v142, v87
	ds_bpermute_b32 v84, v142, v88
	ds_bpermute_b32 v85, v142, v85
	v_max_f32_e32 v78, 0, v78
	v_max_f32_e32 v79, 0, v79
	v_max_f32_e32 v80, 0, v80
	v_max_f32_e32 v77, 0, v77
	v_max_f32_e32 v74, 0, v74
	v_mul_f32_e32 v78, v78, v78
	v_max_f32_e32 v75, 0, v75
	v_mul_f32_e32 v79, v79, v79
	v_max_f32_e32 v76, 0, v76
	v_mul_f32_e32 v80, v80, v80
	v_max_f32_e32 v81, 0, v81
	v_mul_f32_e32 v77, v77, v77
	s_waitcnt lgkmcnt(0)
	global_store_dwordx4 v[94:95], v[82:85], off offset:256
	v_mul_f32_e32 v74, v74, v74
	v_mul_f32_e32 v75, v75, v75
	v_mul_f32_e32 v76, v76, v76
	v_mul_f32_e32 v81, v81, v81
	v_cvt_pk_bf16_f32 v78, v78, v79
	v_cvt_pk_bf16_f32 v79, v80, v81
	v_cvt_pk_bf16_f32 v80, v74, v75
	v_cvt_pk_bf16_f32 v77, v76, v77
	ds_bpermute_b32 v74, v142, v78
	ds_bpermute_b32 v75, v142, v79
	ds_bpermute_b32 v76, v142, v80
	ds_bpermute_b32 v77, v142, v77
	v_or_b32_e32 v78, 48, v147
	v_mad_i64_i32 v[78:79], s[2:3], v78, s85, v[140:141]
	v_max_f32_e32 v70, 0, v70
	v_max_f32_e32 v71, 0, v71
	v_max_f32_e32 v72, 0, v72
	v_max_f32_e32 v69, 0, v69
	v_lshl_add_u64 v[78:79], v[78:79], 0, v[122:123]
	v_max_f32_e32 v66, 0, v66
	v_mul_f32_e32 v70, v70, v70
	v_max_f32_e32 v67, 0, v67
	v_mul_f32_e32 v71, v71, v71
	v_max_f32_e32 v68, 0, v68
	v_mul_f32_e32 v72, v72, v72
	v_max_f32_e32 v73, 0, v73
	v_mul_f32_e32 v69, v69, v69
	s_waitcnt lgkmcnt(0)
	global_store_dwordx4 v[78:79], v[74:77], off
	v_mul_f32_e32 v66, v66, v66
	v_mul_f32_e32 v67, v67, v67
	v_mul_f32_e32 v68, v68, v68
	v_mul_f32_e32 v73, v73, v73
	v_cvt_pk_bf16_f32 v70, v70, v71
	v_cvt_pk_bf16_f32 v71, v72, v73
	v_cvt_pk_bf16_f32 v72, v66, v67
	v_cvt_pk_bf16_f32 v69, v68, v69
	ds_bpermute_b32 v66, v142, v70
	ds_bpermute_b32 v67, v142, v71
	ds_bpermute_b32 v68, v142, v72
	ds_bpermute_b32 v69, v142, v69
	v_max_f32_e32 v62, 0, v62
	v_max_f32_e32 v63, 0, v63
	v_max_f32_e32 v64, 0, v64
	v_max_f32_e32 v61, 0, v61
	v_max_f32_e32 v58, 0, v58
	v_mul_f32_e32 v62, v62, v62
	v_max_f32_e32 v59, 0, v59
	v_mul_f32_e32 v63, v63, v63
	v_max_f32_e32 v60, 0, v60
	v_mul_f32_e32 v64, v64, v64
	v_max_f32_e32 v65, 0, v65
	v_mul_f32_e32 v61, v61, v61
	s_waitcnt lgkmcnt(0)
	global_store_dwordx4 v[78:79], v[66:69], off offset:256
	v_mul_f32_e32 v58, v58, v58
	v_mul_f32_e32 v59, v59, v59
	v_mul_f32_e32 v60, v60, v60
	v_mul_f32_e32 v65, v65, v65
	v_cvt_pk_bf16_f32 v62, v62, v63
	v_cvt_pk_bf16_f32 v63, v64, v65
	v_cvt_pk_bf16_f32 v64, v58, v59
	v_cvt_pk_bf16_f32 v61, v60, v61
	ds_bpermute_b32 v58, v142, v62
	ds_bpermute_b32 v59, v142, v63
	ds_bpermute_b32 v60, v142, v64
	ds_bpermute_b32 v61, v142, v61
	v_add_u32_e32 v62, 0x80, v147
	v_mad_i64_i32 v[62:63], s[2:3], v62, s85, v[140:141]
	v_max_f32_e32 v54, 0, v54
	v_max_f32_e32 v55, 0, v55
	v_max_f32_e32 v56, 0, v56
	v_max_f32_e32 v53, 0, v53
	v_lshl_add_u64 v[62:63], v[62:63], 0, v[122:123]
	v_max_f32_e32 v50, 0, v50
	v_mul_f32_e32 v54, v54, v54
	v_max_f32_e32 v51, 0, v51
	v_mul_f32_e32 v55, v55, v55
	v_max_f32_e32 v52, 0, v52
	v_mul_f32_e32 v56, v56, v56
	v_max_f32_e32 v57, 0, v57
	v_mul_f32_e32 v53, v53, v53
	s_waitcnt lgkmcnt(0)
	global_store_dwordx4 v[62:63], v[58:61], off
	v_mul_f32_e32 v50, v50, v50
	v_mul_f32_e32 v51, v51, v51
	v_mul_f32_e32 v52, v52, v52
	v_mul_f32_e32 v57, v57, v57
	v_cvt_pk_bf16_f32 v54, v54, v55
	v_cvt_pk_bf16_f32 v55, v56, v57
	v_cvt_pk_bf16_f32 v56, v50, v51
	v_cvt_pk_bf16_f32 v53, v52, v53
	ds_bpermute_b32 v50, v142, v54
	ds_bpermute_b32 v51, v142, v55
	ds_bpermute_b32 v52, v142, v56
	ds_bpermute_b32 v53, v142, v53
	v_max_f32_e32 v46, 0, v46
	v_max_f32_e32 v47, 0, v47
	v_max_f32_e32 v48, 0, v48
	v_max_f32_e32 v45, 0, v45
	v_max_f32_e32 v42, 0, v42
	v_mul_f32_e32 v46, v46, v46
	v_max_f32_e32 v43, 0, v43
	v_mul_f32_e32 v47, v47, v47
	v_max_f32_e32 v44, 0, v44
	v_mul_f32_e32 v48, v48, v48
	v_max_f32_e32 v49, 0, v49
	v_mul_f32_e32 v45, v45, v45
	s_waitcnt lgkmcnt(0)
	global_store_dwordx4 v[62:63], v[50:53], off offset:256
	v_mul_f32_e32 v42, v42, v42
	v_mul_f32_e32 v43, v43, v43
	v_mul_f32_e32 v44, v44, v44
	v_mul_f32_e32 v49, v49, v49
	v_cvt_pk_bf16_f32 v46, v46, v47
	v_cvt_pk_bf16_f32 v47, v48, v49
	v_cvt_pk_bf16_f32 v48, v42, v43
	v_cvt_pk_bf16_f32 v45, v44, v45
	ds_bpermute_b32 v42, v142, v46
	ds_bpermute_b32 v43, v142, v47
	ds_bpermute_b32 v44, v142, v48
	ds_bpermute_b32 v45, v142, v45
	v_add_u32_e32 v46, 0x90, v147
	v_mad_i64_i32 v[46:47], s[2:3], v46, s85, v[140:141]
	v_max_f32_e32 v38, 0, v38
	v_max_f32_e32 v39, 0, v39
	v_max_f32_e32 v40, 0, v40
	v_max_f32_e32 v37, 0, v37
	v_lshl_add_u64 v[46:47], v[46:47], 0, v[122:123]
	v_max_f32_e32 v34, 0, v34
	v_mul_f32_e32 v38, v38, v38
	v_max_f32_e32 v35, 0, v35
	v_mul_f32_e32 v39, v39, v39
	v_max_f32_e32 v36, 0, v36
	v_mul_f32_e32 v40, v40, v40
	v_max_f32_e32 v41, 0, v41
	v_mul_f32_e32 v37, v37, v37
	s_waitcnt lgkmcnt(0)
	global_store_dwordx4 v[46:47], v[42:45], off
	v_mul_f32_e32 v34, v34, v34
	v_mul_f32_e32 v35, v35, v35
	v_mul_f32_e32 v36, v36, v36
	v_mul_f32_e32 v41, v41, v41
	v_cvt_pk_bf16_f32 v38, v38, v39
	v_cvt_pk_bf16_f32 v39, v40, v41
	v_cvt_pk_bf16_f32 v40, v34, v35
	v_cvt_pk_bf16_f32 v37, v36, v37
	ds_bpermute_b32 v34, v142, v38
	ds_bpermute_b32 v35, v142, v39
	ds_bpermute_b32 v36, v142, v40
	ds_bpermute_b32 v37, v142, v37
	v_max_f32_e32 v30, 0, v30
	v_max_f32_e32 v31, 0, v31
	v_max_f32_e32 v32, 0, v32
	v_max_f32_e32 v29, 0, v29
	v_max_f32_e32 v26, 0, v26
	v_mul_f32_e32 v30, v30, v30
	v_max_f32_e32 v27, 0, v27
	v_mul_f32_e32 v31, v31, v31
	v_max_f32_e32 v28, 0, v28
	v_mul_f32_e32 v32, v32, v32
	v_max_f32_e32 v33, 0, v33
	v_mul_f32_e32 v29, v29, v29
	s_waitcnt lgkmcnt(0)
	global_store_dwordx4 v[46:47], v[34:37], off offset:256
	v_mul_f32_e32 v26, v26, v26
	v_mul_f32_e32 v27, v27, v27
	v_mul_f32_e32 v28, v28, v28
	v_mul_f32_e32 v33, v33, v33
	v_cvt_pk_bf16_f32 v30, v30, v31
	v_cvt_pk_bf16_f32 v31, v32, v33
	v_cvt_pk_bf16_f32 v32, v26, v27
	v_cvt_pk_bf16_f32 v29, v28, v29
	ds_bpermute_b32 v26, v142, v30
	ds_bpermute_b32 v27, v142, v31
	ds_bpermute_b32 v28, v142, v32
	ds_bpermute_b32 v29, v142, v29
	v_add_u32_e32 v30, 0xa0, v147
	v_mad_i64_i32 v[30:31], s[2:3], v30, s85, v[140:141]
	v_max_f32_e32 v22, 0, v22
	v_max_f32_e32 v23, 0, v23
	v_max_f32_e32 v24, 0, v24
	v_max_f32_e32 v21, 0, v21
	v_lshl_add_u64 v[30:31], v[30:31], 0, v[122:123]
	v_max_f32_e32 v18, 0, v18
	v_mul_f32_e32 v22, v22, v22
	v_max_f32_e32 v19, 0, v19
	v_mul_f32_e32 v23, v23, v23
	v_max_f32_e32 v20, 0, v20
	v_mul_f32_e32 v24, v24, v24
	v_max_f32_e32 v25, 0, v25
	v_mul_f32_e32 v21, v21, v21
	s_waitcnt lgkmcnt(0)
	global_store_dwordx4 v[30:31], v[26:29], off
	v_mul_f32_e32 v18, v18, v18
	v_mul_f32_e32 v19, v19, v19
	v_mul_f32_e32 v20, v20, v20
	v_mul_f32_e32 v25, v25, v25
	v_cvt_pk_bf16_f32 v22, v22, v23
	v_cvt_pk_bf16_f32 v23, v24, v25
	v_cvt_pk_bf16_f32 v24, v18, v19
	v_cvt_pk_bf16_f32 v21, v20, v21
	ds_bpermute_b32 v18, v142, v22
	ds_bpermute_b32 v19, v142, v23
	ds_bpermute_b32 v20, v142, v24
	ds_bpermute_b32 v21, v142, v21
	v_max_f32_e32 v14, 0, v14
	v_max_f32_e32 v15, 0, v15
	v_max_f32_e32 v16, 0, v16
	v_max_f32_e32 v13, 0, v13
	v_max_f32_e32 v10, 0, v10
	v_mul_f32_e32 v14, v14, v14
	v_max_f32_e32 v11, 0, v11
	v_mul_f32_e32 v15, v15, v15
	v_max_f32_e32 v12, 0, v12
	v_mul_f32_e32 v16, v16, v16
	v_max_f32_e32 v17, 0, v17
	v_mul_f32_e32 v13, v13, v13
	s_waitcnt lgkmcnt(0)
	global_store_dwordx4 v[30:31], v[18:21], off offset:256
	v_mul_f32_e32 v10, v10, v10
	v_mul_f32_e32 v11, v11, v11
	v_mul_f32_e32 v12, v12, v12
	v_mul_f32_e32 v17, v17, v17
	v_cvt_pk_bf16_f32 v14, v14, v15
	v_cvt_pk_bf16_f32 v15, v16, v17
	v_cvt_pk_bf16_f32 v16, v10, v11
	v_cvt_pk_bf16_f32 v13, v12, v13
	ds_bpermute_b32 v10, v142, v14
	ds_bpermute_b32 v11, v142, v15
	ds_bpermute_b32 v12, v142, v16
	ds_bpermute_b32 v13, v142, v13
	v_add_u32_e32 v14, 0xb0, v147
	v_mad_i64_i32 v[14:15], s[2:3], v14, s85, v[140:141]
	v_max_f32_e32 v6, 0, v6
	v_max_f32_e32 v7, 0, v7
	v_max_f32_e32 v8, 0, v8
	v_max_f32_e32 v5, 0, v5
	v_lshl_add_u64 v[14:15], v[14:15], 0, v[122:123]
	v_max_f32_e32 v2, 0, v2
	v_mul_f32_e32 v6, v6, v6
	v_max_f32_e32 v3, 0, v3
	v_mul_f32_e32 v7, v7, v7
	v_max_f32_e32 v4, 0, v4
	v_mul_f32_e32 v8, v8, v8
	v_max_f32_e32 v9, 0, v9
	v_mul_f32_e32 v5, v5, v5
	s_waitcnt lgkmcnt(0)
	global_store_dwordx4 v[14:15], v[10:13], off
	v_mul_f32_e32 v2, v2, v2
	v_mul_f32_e32 v3, v3, v3
	v_mul_f32_e32 v4, v4, v4
	v_mul_f32_e32 v9, v9, v9
	v_cvt_pk_bf16_f32 v6, v6, v7
	v_cvt_pk_bf16_f32 v7, v8, v9
	v_cvt_pk_bf16_f32 v8, v2, v3
	v_cvt_pk_bf16_f32 v5, v4, v5
	ds_bpermute_b32 v2, v142, v6
	ds_bpermute_b32 v3, v142, v7
	ds_bpermute_b32 v4, v142, v8
	ds_bpermute_b32 v5, v142, v5
	s_andn2_b64 vcc, exec, s[46:47]
	s_mov_b64 s[2:3], -1
	s_waitcnt lgkmcnt(0)
	global_store_dwordx4 v[14:15], v[2:5], off offset:256
	s_cbranch_vccnz .LBB0_759
	s_andn2_b64 vcc, exec, s[12:13]
	s_cbranch_vccnz .LBB0_758
	s_barrier
	s_branch .LBB0_758
